# grid barrier top level: leaders arrive with a non-returning atomic and poll the counter itself for (round+1)*nXCD; removes one memory round trip and the generation word from every barrier
# speedup vs baseline: 1.0284x; 1.0008x over previous
.LBB0_136:
	s_andn2_saveexec_b64 s[2:3], s[2:3]
	s_cbranch_execz .LBB0_156
	s_mov_b64 s[2:3], exec
	buffer_wbl2 sc1
	s_waitcnt lgkmcnt(0)
	s_waitcnt vmcnt(0)
	v_readfirstlane_b32 s98, v1
	v_readfirstlane_b32 s99, v0
	s_add_u32 s98, s98, 1
	s_mul_i32 s98, s98, s99
	v_readlane_b32 s100, v254, 52
	v_readlane_b32 s101, v254, 53
	v_mov_b32_e32 v2, 0
	v_mov_b32_e32 v3, 1
	s_nop 3
	global_atomic_add v2, v3, s[100:101]
	s_mov_b32 s99, 0
.Lmy_top_spin_1:
	global_load_dword v1, v2, s[100:101] sc1
	s_waitcnt vmcnt(0)
	v_readfirstlane_b32 s2, v1
	s_cmp_lt_u32 s2, s98
	s_cbranch_scc0 .Lmy_top_done_1
	s_sleep 1
	s_add_u32 s99, s99, 1
	s_cmp_lt_u32 s99, 0x100000
	s_cbranch_scc1 .Lmy_top_spin_1
.Lmy_top_done_1:
	s_mov_b64 s[2:3], exec
.LBB0_153:
	s_or_b64 exec, exec, s[2:3]
	s_mov_b64 s[2:3], exec
	v_mbcnt_lo_u32_b32 v0, s2, 0
	v_mbcnt_hi_u32_b32 v0, s3, v0
	s_mov_b32 s7, 0
	v_cmp_eq_u32_e32 vcc, 0, v0
	s_waitcnt vmcnt(0)
	s_and_saveexec_b64 s[4:5], vcc
	s_cbranch_execz .LBB0_155
	s_add_i32 s6, s18, 0x900
	s_lshl_b64 s[6:7], s[6:7], 2
	v_readlane_b32 s8, v253, 5
	v_readlane_b32 s9, v253, 6
	s_add_u32 s6, s8, s6
	s_addc_u32 s7, s9, s7
	s_bcnt1_i32_b64 s2, s[2:3]
	v_mov_b32_e32 v0, 0
	v_mov_b32_e32 v1, s2
	global_atomic_add v0, v1, s[6:7]

.LBB0_220:
	s_andn2_saveexec_b64 s[4:5], s[4:5]
	s_cbranch_execz .LBB0_240
	s_mov_b64 s[4:5], exec
	buffer_wbl2 sc1
	s_waitcnt lgkmcnt(0)
	s_waitcnt vmcnt(0)
	v_readfirstlane_b32 s98, v1
	v_readfirstlane_b32 s99, v0
	s_add_u32 s98, s98, 1
	s_mul_i32 s98, s98, s99
	v_readlane_b32 s100, v254, 52
	v_readlane_b32 s101, v254, 53
	v_mov_b32_e32 v2, 0
	v_mov_b32_e32 v3, 1
	s_nop 3
	global_atomic_add v2, v3, s[100:101]
	s_mov_b32 s99, 0
.Lmy_top_spin_2:
	global_load_dword v1, v2, s[100:101] sc1
	s_waitcnt vmcnt(0)
	v_readfirstlane_b32 s4, v1
	s_cmp_lt_u32 s4, s98
	s_cbranch_scc0 .Lmy_top_done_2
	s_sleep 1
	s_add_u32 s99, s99, 1
	s_cmp_lt_u32 s99, 0x100000
	s_cbranch_scc1 .Lmy_top_spin_2
.Lmy_top_done_2:
	s_mov_b64 s[4:5], exec
.LBB0_237:
	s_or_b64 exec, exec, s[4:5]
	s_mov_b64 s[4:5], exec
	v_mbcnt_lo_u32_b32 v0, s4, 0
	v_mbcnt_hi_u32_b32 v0, s5, v0
	s_mov_b32 s9, 0
	v_cmp_eq_u32_e32 vcc, 0, v0
	s_waitcnt vmcnt(0)
	s_and_saveexec_b64 s[6:7], vcc
	s_cbranch_execz .LBB0_239
	s_add_i32 s8, s20, 0x900
	s_lshl_b64 s[8:9], s[8:9], 2
	v_readlane_b32 s10, v253, 5
	v_readlane_b32 s11, v253, 6
	s_add_u32 s8, s10, s8
	s_addc_u32 s9, s11, s9
	s_bcnt1_i32_b64 s4, s[4:5]
	v_mov_b32_e32 v0, 0
	v_mov_b32_e32 v1, s4
	global_atomic_add v0, v1, s[8:9]

.Lmy_top_done_3:
	s_mov_b64 s[4:5], exec
.LBB0_335:
	s_or_b64 exec, exec, s[4:5]
	s_mov_b64 s[4:5], exec
	v_mbcnt_lo_u32_b32 v0, s4, 0
	v_mbcnt_hi_u32_b32 v0, s5, v0
	s_mov_b32 s9, 0
	v_cmp_eq_u32_e32 vcc, 0, v0
	s_waitcnt vmcnt(0)
	s_and_saveexec_b64 s[6:7], vcc
	s_cbranch_execz .LBB0_337
	s_add_i32 s8, s20, 0x900
	s_lshl_b64 s[8:9], s[8:9], 2
	v_readlane_b32 s10, v253, 5
	v_readlane_b32 s11, v253, 6
	s_add_u32 s8, s10, s8
	s_addc_u32 s9, s11, s9
	s_bcnt1_i32_b64 s4, s[4:5]
	v_mov_b32_e32 v0, 0
	v_mov_b32_e32 v1, s4
	global_atomic_add v0, v1, s[8:9]

.Lmy_top_done_4:
	s_mov_b64 s[2:3], exec
.LBB0_412:
	s_or_b64 exec, exec, s[2:3]
	s_mov_b64 s[2:3], exec
	v_mbcnt_lo_u32_b32 v0, s2, 0
	v_mbcnt_hi_u32_b32 v0, s3, v0
	s_mov_b32 s7, 0
	v_cmp_eq_u32_e32 vcc, 0, v0
	s_waitcnt vmcnt(0)
	s_and_saveexec_b64 s[4:5], vcc
	s_cbranch_execz .LBB0_414
	s_add_i32 s6, s20, 0x900
	s_lshl_b64 s[6:7], s[6:7], 2
	v_readlane_b32 s8, v253, 5
	v_readlane_b32 s9, v253, 6
	s_add_u32 s6, s8, s6
	s_addc_u32 s7, s9, s7
	s_bcnt1_i32_b64 s2, s[2:3]
	v_mov_b32_e32 v0, 0
	v_mov_b32_e32 v1, s2
	global_atomic_add v0, v1, s[6:7]

.Lmy_top_done_5:
	s_mov_b64 s[4:5], exec
.LBB0_606:
	s_or_b64 exec, exec, s[4:5]
	s_mov_b64 s[4:5], exec
	v_mbcnt_lo_u32_b32 v0, s4, 0
	v_mbcnt_hi_u32_b32 v0, s5, v0
	s_mov_b32 s9, 0
	v_cmp_eq_u32_e32 vcc, 0, v0
	s_waitcnt vmcnt(0)
	s_and_saveexec_b64 s[6:7], vcc
	s_cbranch_execz .LBB0_608
	s_add_i32 s8, s20, 0x900
	s_lshl_b64 s[8:9], s[8:9], 2
	v_readlane_b32 s10, v253, 5
	v_readlane_b32 s11, v253, 6
	s_add_u32 s8, s10, s8
	s_addc_u32 s9, s11, s9
	s_bcnt1_i32_b64 s4, s[4:5]
	v_mov_b32_e32 v0, 0
	v_mov_b32_e32 v1, s4
	global_atomic_add v0, v1, s[8:9]

.Lmy_top_done_6:
	s_mov_b64 s[2:3], exec
.LBB0_755:
	s_or_b64 exec, exec, s[2:3]
	s_mov_b64 s[2:3], exec
	v_mbcnt_lo_u32_b32 v0, s2, 0
	v_mbcnt_hi_u32_b32 v0, s3, v0
	s_mov_b32 s7, 0
	v_cmp_eq_u32_e32 vcc, 0, v0
	s_waitcnt vmcnt(0)
	s_and_saveexec_b64 s[4:5], vcc
	s_cbranch_execz .LBB0_757
	s_add_i32 s6, s20, 0x900
	s_lshl_b64 s[6:7], s[6:7], 2
	v_readlane_b32 s8, v253, 5
	v_readlane_b32 s9, v253, 6
	s_add_u32 s6, s8, s6
	s_addc_u32 s7, s9, s7
	s_bcnt1_i32_b64 s2, s[2:3]
	v_mov_b32_e32 v0, 0
	v_mov_b32_e32 v1, s2
	global_atomic_add v0, v1, s[6:7]

.Lmy_top_done_7:
	s_mov_b64 s[2:3], exec
.LBB0_833:
	s_or_b64 exec, exec, s[2:3]
	s_mov_b64 s[2:3], exec
	v_mbcnt_lo_u32_b32 v0, s2, 0
	v_mbcnt_hi_u32_b32 v0, s3, v0
	s_mov_b32 s7, 0
	v_cmp_eq_u32_e32 vcc, 0, v0
	s_waitcnt vmcnt(0)
	s_and_saveexec_b64 s[4:5], vcc
	s_cbranch_execz .LBB0_835
	s_add_i32 s6, s20, 0x900
	s_lshl_b64 s[6:7], s[6:7], 2
	v_readlane_b32 s8, v253, 5
	v_readlane_b32 s9, v253, 6
	s_add_u32 s6, s8, s6
	s_addc_u32 s7, s9, s7
	s_bcnt1_i32_b64 s2, s[2:3]
	v_mov_b32_e32 v0, 0
	v_mov_b32_e32 v1, s2
	global_atomic_add v0, v1, s[6:7]

.Lmy_top_done_8:
	s_mov_b64 s[4:5], exec
.LBB0_941:
	s_or_b64 exec, exec, s[4:5]
	s_mov_b64 s[4:5], exec
	v_mbcnt_lo_u32_b32 v0, s4, 0
	v_mbcnt_hi_u32_b32 v0, s5, v0
	s_mov_b32 s9, 0
	v_cmp_eq_u32_e32 vcc, 0, v0
	s_waitcnt vmcnt(0)
	s_and_saveexec_b64 s[6:7], vcc
	s_cbranch_execz .LBB0_943
	s_add_i32 s8, s20, 0x900
	s_lshl_b64 s[8:9], s[8:9], 2
	v_readlane_b32 s10, v253, 5
	v_readlane_b32 s11, v253, 6
	s_add_u32 s8, s10, s8
	s_addc_u32 s9, s11, s9
	s_bcnt1_i32_b64 s4, s[4:5]
	v_mov_b32_e32 v0, 0
	v_mov_b32_e32 v1, s4
	global_atomic_add v0, v1, s[8:9]

.Lmy_top_done_9:
	s_mov_b64 s[2:3], exec
.LBB0_1014:
	s_or_b64 exec, exec, s[2:3]
	s_mov_b64 s[2:3], exec
	v_mbcnt_lo_u32_b32 v0, s2, 0
	v_mbcnt_hi_u32_b32 v0, s3, v0
	s_mov_b32 s7, 0
	v_cmp_eq_u32_e32 vcc, 0, v0
	s_waitcnt vmcnt(0)
	s_and_saveexec_b64 s[4:5], vcc
	s_cbranch_execz .LBB0_1016
	s_add_i32 s6, s20, 0x900
	s_lshl_b64 s[6:7], s[6:7], 2
	v_readlane_b32 s8, v253, 5
	v_readlane_b32 s9, v253, 6
	s_add_u32 s6, s8, s6
	s_addc_u32 s7, s9, s7
	s_bcnt1_i32_b64 s2, s[2:3]
	v_mov_b32_e32 v0, 0
	v_mov_b32_e32 v1, s2
	global_atomic_add v0, v1, s[6:7]
